# attnC: V^T fragment reads issued as early as buffers allow; group barrier arrival before PV MFMA 10 (on top of the attnA version)
# baseline (speedup 1.0000x reference)
.LBB0_1057:
	v_cmp_le_i32_e32 vcc, s12, v187
	s_and_saveexec_b64 s[10:11], vcc
	s_cbranch_execz .LBB0_1059
	s_lshl_b32 s12, s12, 15
	s_and_b32 s12, s12, 0x8000
	s_add_i32 s12, s80, s12
	v_add3_u32 v220, s12, v186, v190
	v_add_u32_e32 v221, v220, v199
	v_add_u32_e32 v222, v220, v200
	v_add_u32_e32 v223, v220, v201
	v_add_u32_e32 v224, v220, v202
	v_add_u32_e32 v225, v220, v203
	v_add_u32_e32 v226, v220, v216
	v_add_u32_e32 v227, v220, v217
	v_add_u32_e32 v228, v220, v218
	v_lshrrev_b32_e32 v229, v189, v168
	v_lshrrev_b32_e32 v230, v189, v169
	v_add3_u32 v0, s12, v191, v188
	ds_read_b128 v[2:5], v0
	ds_read_b128 v[8:11], v0 offset:8192
	v_add3_u32 v0, s12, v192, v188
	ds_read_b128 v[12:15], v0
	s_waitcnt lgkmcnt(2)
	v_mfma_f32_32x32x16_bf16 v[112:127], v[2:5], v[156:159], v[16:31]
	ds_read_b128 v[2:5], v0 offset:8192
	s_waitcnt lgkmcnt(2)
	v_mfma_f32_32x32x16_bf16 v[96:111], v[8:11], v[156:159], v[16:31]
	v_add3_u32 v0, s12, v193, v188
	ds_read_b128 v[8:11], v0
	s_waitcnt lgkmcnt(2)
	v_mfma_f32_32x32x16_bf16 v[112:127], v[12:15], v[128:131], v[112:127]
	ds_read_b128 v[12:15], v0 offset:8192
	s_waitcnt lgkmcnt(2)
	v_mfma_f32_32x32x16_bf16 v[96:111], v[2:5], v[128:131], v[96:111]
	v_add3_u32 v0, s12, v194, v188
	ds_read_b128 v[2:5], v0
	s_waitcnt lgkmcnt(2)
	v_mfma_f32_32x32x16_bf16 v[112:127], v[8:11], v[132:135], v[112:127]
	ds_read_b128 v[8:11], v0 offset:8192
	s_waitcnt lgkmcnt(2)
	v_mfma_f32_32x32x16_bf16 v[96:111], v[12:15], v[132:135], v[96:111]
	v_add3_u32 v0, s12, v195, v188
	ds_read_b128 v[12:15], v0
	s_waitcnt lgkmcnt(2)
	v_mfma_f32_32x32x16_bf16 v[112:127], v[2:5], v[136:139], v[112:127]
	ds_read_b128 v[2:5], v0 offset:8192
	s_waitcnt lgkmcnt(2)
	v_mfma_f32_32x32x16_bf16 v[96:111], v[8:11], v[136:139], v[96:111]
	v_add3_u32 v0, s12, v196, v188
	ds_read_b128 v[8:11], v0
	s_waitcnt lgkmcnt(2)
	v_mfma_f32_32x32x16_bf16 v[112:127], v[12:15], v[140:143], v[112:127]
	ds_read_b128 v[12:15], v0 offset:8192
	s_waitcnt lgkmcnt(2)
	v_mfma_f32_32x32x16_bf16 v[96:111], v[2:5], v[140:143], v[96:111]
	v_add3_u32 v0, s12, v197, v188
	ds_read_b128 v[2:5], v0
	s_waitcnt lgkmcnt(2)
	v_mfma_f32_32x32x16_bf16 v[112:127], v[8:11], v[144:147], v[112:127]
	ds_read_b128 v[8:11], v0 offset:8192
	s_waitcnt lgkmcnt(2)
	v_mfma_f32_32x32x16_bf16 v[96:111], v[12:15], v[144:147], v[96:111]
	v_add3_u32 v0, s12, v198, v188
	ds_read_b128 v[12:15], v0
	s_waitcnt lgkmcnt(2)
	v_mfma_f32_32x32x16_bf16 v[112:127], v[2:5], v[148:151], v[112:127]
	ds_read_b128 v[2:5], v0 offset:8192
	s_waitcnt lgkmcnt(2)
	v_mfma_f32_32x32x16_bf16 v[96:111], v[8:11], v[148:151], v[96:111]
	s_waitcnt lgkmcnt(1)
	v_mfma_f32_32x32x16_bf16 v[112:127], v[12:15], v[152:155], v[112:127]
	s_waitcnt lgkmcnt(0)
	v_mfma_f32_32x32x16_bf16 v[96:111], v[2:5], v[152:155], v[96:111]
	ds_read_b64 v[8:9], v221 offset:16384
	ds_read_b64 v[10:11], v222 offset:16384
	ds_read_b64 v[12:13], v221 offset:20480
	ds_read_b64 v[14:15], v222 offset:20480
	ds_read_b64 v[236:237], v221 offset:28672
	ds_read_b64 v[238:239], v222 offset:28672
	s_nop 3
	v_exp_f32_e32 v112, v112
	v_exp_f32_e32 v113, v113
	v_exp_f32_e32 v114, v114
	v_exp_f32_e32 v115, v115
	v_exp_f32_e32 v116, v116
	v_exp_f32_e32 v117, v117
	v_exp_f32_e32 v118, v118
	v_exp_f32_e32 v119, v119
	v_bfe_i32 v231, v229, 0, 1
	v_and_b32_e32 v112, v112, v231
	v_bfe_i32 v232, v229, 1, 1
	v_and_b32_e32 v113, v113, v232
	v_bfe_i32 v231, v229, 2, 1
	v_and_b32_e32 v114, v114, v231
	v_bfe_i32 v232, v229, 3, 1
	v_and_b32_e32 v115, v115, v232
	v_bfe_i32 v231, v229, 8, 1
	v_and_b32_e32 v116, v116, v231
	v_bfe_i32 v232, v229, 9, 1
	v_and_b32_e32 v117, v117, v232
	v_bfe_i32 v231, v229, 10, 1
	v_and_b32_e32 v118, v118, v231
	v_bfe_i32 v232, v229, 11, 1
	v_and_b32_e32 v119, v119, v232
	v_cvt_pk_bf16_f32 v2, v112, v113
	v_cvt_pk_bf16_f32 v3, v114, v115
	v_cvt_pk_bf16_f32 v4, v116, v117
	v_cvt_pk_bf16_f32 v5, v118, v119
	v_add_f32_e32 v0, 0, v112
	v_add_f32_e32 v0, v113, v0
	v_add_f32_e32 v0, v114, v0
	v_add_f32_e32 v0, v115, v0
	v_add_f32_e32 v0, v116, v0
	v_add_f32_e32 v0, v117, v0
	v_add_f32_e32 v0, v118, v0
	v_add_f32_e32 v0, v119, v0
	ds_read_b64 v[240:241], v221 offset:24576
	ds_read_b64 v[242:243], v222 offset:24576
	ds_read_b64 v[244:245], v223 offset:16384
	ds_read_b64 v[246:247], v224 offset:16384
	s_waitcnt lgkmcnt(8)
	v_mfma_f32_32x32x16_bf16 v[80:95], v[8:11], v[2:5], v[80:95]
	ds_read_b64 v[112:113], v223 offset:20480
	ds_read_b64 v[114:115], v224 offset:20480
	ds_read_b64 v[116:117], v223 offset:24576
	ds_read_b64 v[118:119], v224 offset:24576
	ds_read_b64 v[8:9], v223 offset:28672
	ds_read_b64 v[10:11], v224 offset:28672
	v_exp_f32_e32 v120, v120
	v_exp_f32_e32 v121, v121
	s_waitcnt lgkmcnt(12)
	v_mfma_f32_32x32x16_bf16 v[64:79], v[12:15], v[2:5], v[64:79]
	ds_read_b64 v[12:13], v225 offset:16384
	ds_read_b64 v[14:15], v226 offset:16384
	v_exp_f32_e32 v122, v122
	v_exp_f32_e32 v123, v123
	v_bfe_i32 v231, v229, 16, 1
	v_and_b32_e32 v120, v120, v231
	v_bfe_i32 v232, v229, 17, 1
	v_and_b32_e32 v121, v121, v232
	v_add_f32_e32 v0, v120, v0
	v_add_f32_e32 v0, v121, v0
	s_waitcnt lgkmcnt(12)
	v_mfma_f32_32x32x16_bf16 v[32:47], v[236:239], v[2:5], v[32:47]
	ds_read_b64 v[236:237], v225 offset:20480
	ds_read_b64 v[238:239], v226 offset:20480
	v_exp_f32_e32 v124, v124
	v_exp_f32_e32 v125, v125
	v_bfe_i32 v231, v229, 18, 1
	v_and_b32_e32 v122, v122, v231
	v_bfe_i32 v232, v229, 19, 1
	v_and_b32_e32 v123, v123, v232
	v_add_f32_e32 v0, v122, v0
	v_add_f32_e32 v0, v123, v0
	s_waitcnt lgkmcnt(12)
	v_mfma_f32_32x32x16_bf16 v[48:63], v[240:243], v[2:5], v[48:63]
	ds_read_b64 v[240:241], v225 offset:24576
	ds_read_b64 v[242:243], v226 offset:24576
	v_exp_f32_e32 v126, v126
	v_exp_f32_e32 v127, v127
	v_bfe_i32 v231, v229, 24, 1
	v_and_b32_e32 v124, v124, v231
	v_bfe_i32 v232, v229, 25, 1
	v_and_b32_e32 v125, v125, v232
	v_add_f32_e32 v0, v124, v0
	v_add_f32_e32 v0, v125, v0
	v_bfe_i32 v231, v229, 26, 1
	v_and_b32_e32 v126, v126, v231
	v_bfe_i32 v232, v229, 27, 1
	v_and_b32_e32 v127, v127, v232
	v_add_f32_e32 v0, v126, v0
	v_add_f32_e32 v0, v127, v0
	v_cvt_pk_bf16_f32 v2, v120, v121
	v_cvt_pk_bf16_f32 v3, v122, v123
	v_cvt_pk_bf16_f32 v4, v124, v125
	v_cvt_pk_bf16_f32 v5, v126, v127
	s_nop 1
	ds_read_b64 v[120:121], v225 offset:28672
	ds_read_b64 v[122:123], v226 offset:28672
	ds_read_b64 v[124:125], v227 offset:16384
	ds_read_b64 v[126:127], v228 offset:16384
	s_waitcnt lgkmcnt(15)
	v_mfma_f32_32x32x16_bf16 v[80:95], v[244:247], v[2:5], v[80:95]
	ds_read_b64 v[244:245], v227 offset:20480
	ds_read_b64 v[246:247], v228 offset:20480
	v_exp_f32_e32 v96, v96
	v_exp_f32_e32 v97, v97
	s_waitcnt lgkmcnt(15)
	v_mfma_f32_32x32x16_bf16 v[64:79], v[112:115], v[2:5], v[64:79]
	ds_read_b64 v[112:113], v227 offset:24576
	ds_read_b64 v[114:115], v228 offset:24576
	v_exp_f32_e32 v98, v98
	v_exp_f32_e32 v99, v99
	v_bfe_i32 v231, v230, 0, 1
	v_and_b32_e32 v96, v96, v231
	v_bfe_i32 v232, v230, 1, 1
	v_and_b32_e32 v97, v97, v232
	v_add_f32_e32 v0, v96, v0
	v_add_f32_e32 v0, v97, v0
	s_waitcnt lgkmcnt(15)
	v_mfma_f32_32x32x16_bf16 v[48:63], v[116:119], v[2:5], v[48:63]
	ds_read_b64 v[116:117], v227 offset:28672
	ds_read_b64 v[118:119], v228 offset:28672
	v_exp_f32_e32 v100, v100
	v_exp_f32_e32 v101, v101
	v_bfe_i32 v231, v230, 2, 1
	v_and_b32_e32 v98, v98, v231
	v_bfe_i32 v232, v230, 3, 1
	v_and_b32_e32 v99, v99, v232
	v_add_f32_e32 v0, v98, v0
	v_add_f32_e32 v0, v99, v0
	s_waitcnt lgkmcnt(15)
	v_mfma_f32_32x32x16_bf16 v[32:47], v[8:11], v[2:5], v[32:47]
	v_exp_f32_e32 v102, v102
	v_exp_f32_e32 v103, v103
	v_bfe_i32 v231, v230, 8, 1
	v_and_b32_e32 v100, v100, v231
	v_bfe_i32 v232, v230, 9, 1
	v_and_b32_e32 v101, v101, v232
	v_add_f32_e32 v0, v100, v0
	v_add_f32_e32 v0, v101, v0
	v_bfe_i32 v231, v230, 10, 1
	v_and_b32_e32 v102, v102, v231
	v_bfe_i32 v232, v230, 11, 1
	v_and_b32_e32 v103, v103, v232
	v_add_f32_e32 v0, v102, v0
	v_add_f32_e32 v0, v103, v0
	v_cvt_pk_bf16_f32 v2, v96, v97
	v_cvt_pk_bf16_f32 v3, v98, v99
	v_cvt_pk_bf16_f32 v4, v100, v101
	v_cvt_pk_bf16_f32 v5, v102, v103
	s_nop 1
	s_waitcnt lgkmcnt(14)
	v_mfma_f32_32x32x16_bf16 v[80:95], v[12:15], v[2:5], v[80:95]
	v_exp_f32_e32 v104, v104
	v_exp_f32_e32 v105, v105
	s_waitcnt lgkmcnt(12)
	v_mfma_f32_32x32x16_bf16 v[64:79], v[236:239], v[2:5], v[64:79]
	v_exp_f32_e32 v106, v106
	v_exp_f32_e32 v107, v107
	v_bfe_i32 v231, v230, 16, 1
	v_and_b32_e32 v104, v104, v231
	v_bfe_i32 v232, v230, 17, 1
	v_and_b32_e32 v105, v105, v232
	v_add_f32_e32 v0, v104, v0
	v_add_f32_e32 v0, v105, v0
	s_waitcnt vmcnt(0) lgkmcnt(0)
	s_mov_b64 s[24:25], exec
	s_mov_b64 exec, 1
	v_mov_b32_e32 v248, s33
	v_mov_b32_e32 v249, 1
	ds_add_u32 v248, v249 offset:8
	s_mov_b64 exec, s[24:25]
	s_waitcnt lgkmcnt(10)
	v_mfma_f32_32x32x16_bf16 v[48:63], v[240:243], v[2:5], v[48:63]
	v_exp_f32_e32 v108, v108
	v_exp_f32_e32 v109, v109
	v_bfe_i32 v231, v230, 18, 1
	v_and_b32_e32 v106, v106, v231
	v_bfe_i32 v232, v230, 19, 1
	v_and_b32_e32 v107, v107, v232
	v_add_f32_e32 v0, v106, v0
	v_add_f32_e32 v0, v107, v0
	s_waitcnt lgkmcnt(8)
	v_mfma_f32_32x32x16_bf16 v[32:47], v[120:123], v[2:5], v[32:47]
	v_exp_f32_e32 v110, v110
	v_exp_f32_e32 v111, v111
	v_bfe_i32 v231, v230, 24, 1
	v_and_b32_e32 v108, v108, v231
	v_bfe_i32 v232, v230, 25, 1
	v_and_b32_e32 v109, v109, v232
	v_add_f32_e32 v0, v108, v0
	v_add_f32_e32 v0, v109, v0
	v_bfe_i32 v231, v230, 26, 1
	v_and_b32_e32 v110, v110, v231
	v_bfe_i32 v232, v230, 27, 1
	v_and_b32_e32 v111, v111, v232
	v_add_f32_e32 v0, v110, v0
	v_add_f32_e32 v0, v111, v0
	v_cvt_pk_bf16_f32 v2, v104, v105
	v_cvt_pk_bf16_f32 v3, v106, v107
	v_cvt_pk_bf16_f32 v4, v108, v109
	v_cvt_pk_bf16_f32 v5, v110, v111
	s_nop 1
	s_waitcnt lgkmcnt(6)
	v_mfma_f32_32x32x16_bf16 v[80:95], v[124:127], v[2:5], v[80:95]
	s_waitcnt lgkmcnt(4)
	v_mfma_f32_32x32x16_bf16 v[64:79], v[244:247], v[2:5], v[64:79]
	s_waitcnt lgkmcnt(2)
	v_mfma_f32_32x32x16_bf16 v[48:63], v[112:115], v[2:5], v[48:63]
	s_waitcnt lgkmcnt(0)
	v_mfma_f32_32x32x16_bf16 v[32:47], v[116:119], v[2:5], v[32:47]
	v_add_f32_e32 v219, v219, v0
	s_branch .LBB0_1062
